# back-edge rotation (7.11) on attention modes 0/1: loop-carried moves and exit test hoisted in front of the tile barrier, single taken branch after the barrier
# speedup vs baseline: 1.0206x; 1.0018x over previous
; #define LAS __attribute__((address_space(3)))
; template <int MODE> __device__ __forceinline__ void attn_unit4(LAS unsigned char* lds, const int uidx, const AttnArgs& A) {
;     ...
;     { const LAS unsigned char* vb_ = lds + VBASE + vs_cur * VSTG + vfrag; const LAS unsigned char* kb_ = lds; bf16x8 fa[NM];
; #pragma unroll
;       for (int i = 0; i < PF; ++i) { A3_LOADF(i); fan[i] = fa[i]; } }
;     if (wid >= 4) __builtin_amdgcn_s_setprio(1);
;     int t = t0;
;     for (; t + 1 < t1; t += 2) {
;         A3_BODY(t, s0, s1, n0, n1);
;         A3_BODY(t + 1, n0, n1, s0, s1);
;     }
.LBB0_967:
	s_add_u32 s0, s0, 0x10000
	s_addc_u32 s1, s1, 0
	s_add_u32 s4, s4, 0x18000
	v_fmac_f32_e32 v209, v208, v188
	s_addc_u32 s5, s5, 0
	v_fmac_f32_e32 v143, v209, v190
	s_cmpk_lt_u32 s41, 0x7f
	s_cbranch_scc0 .Lrot1_exit
	v_mov_b32_e32 v208, v143
	v_mov_b32_e32 v188, v142
	s_mov_b32 s30, s39
	s_mov_b32 s39, s62
	s_mov_b32 s62, s40
	s_mov_b32 s40, s30
	v_cmp_neq_f32_e32 vcc, 1.0, v190
	s_waitcnt lgkmcnt(0)
	s_barrier
	s_cbranch_vccz .LBB0_959
	s_branch .LBB0_958
.Lrot1_exit:
	s_waitcnt lgkmcnt(0)
	s_barrier
	s_branch .LBB0_1007

; #define LAS __attribute__((address_space(3)))
; template <int MODE> __device__ __forceinline__ void attn_unit4(LAS unsigned char* lds, const int uidx, const AttnArgs& A) {
;     ...
;     { const LAS unsigned char* vb_ = lds + VBASE + vs_cur * VSTG + vfrag; const LAS unsigned char* kb_ = lds; bf16x8 fa[NM];
; #pragma unroll
;       for (int i = 0; i < PF; ++i) { A3_LOADF(i); fan[i] = fa[i]; } }
;     if (wid >= 4) __builtin_amdgcn_s_setprio(1);
;     int t = t0;
;     for (; t + 1 < t1; t += 2) {
;         A3_BODY(t, s0, s1, n0, n1);
;         A3_BODY(t + 1, n0, n1, s0, s1);
;     }
.Lnc_b_skip:
	s_add_i32 s76, s76, 2
	s_addk_i32 s75, 0x80
	v_fmac_f32_e32 v199, v198, v0
	s_add_u32 s8, s8, 0x9a000
	v_fmac_f32_e32 v163, v199, v180
	s_addc_u32 s9, s9, 0
	s_andn2_b64 vcc, exec, s[52:53]
	s_cbranch_vccz .Lrot0_exit
	v_mov_b32_e32 v198, v163
	v_mov_b32_e32 v0, v162
	s_mov_b32 s0, s72
	s_mov_b32 s72, s77
	s_mov_b32 s77, s74
	s_mov_b32 s74, s0
	v_cmp_neq_f32_e32 vcc, 1.0, v180
	s_waitcnt lgkmcnt(0)
	s_barrier
	s_cbranch_vccz .LBB0_985
	s_branch .LBB0_984
.Lrot0_exit:
	s_waitcnt lgkmcnt(0)
	s_barrier
